# holdB plus one static s_setprio 1 for waves 4-7 at kernel entry
# baseline (speedup 1.0000x reference)
_Z14fwd_megakernel4Args:
	v_readfirstlane_b32 s98, v0
	s_bfe_u32 s98, s98, 0x10008
	s_cmp_eq_u32 s98, 0
	s_cbranch_scc1 .Lprio_done
	s_setprio 1
.Lprio_done:
	s_load_dwordx2 s[12:13], s[0:1], 0x90
	s_load_dwordx4 s[60:63], s[0:1], 0x80
	s_add_u32 s4, s0, 0x98
	v_and_b32_e32 v210, 0x3ff, v0
	s_mov_b32 s56, s2
	s_addc_u32 s5, s1, 0
	v_cmp_gt_u32_e32 vcc, 16, v210
	s_and_saveexec_b64 s[2:3], vcc
	v_lshl_add_u32 v1, v210, 2, 0
	v_add_u32_e32 v1, 0x277c0, v1
	v_mov_b32_e32 v2, 0
	ds_write_b32 v1, v2
	s_or_b64 exec, exec, s[2:3]
	s_load_dwordx2 s[90:91], s[0:1], 0x98
	s_load_dword s87, s[0:1], 0xa0
	s_waitcnt lgkmcnt(0)
	s_barrier
	s_add_u32 s10, s12, 0x500000
	s_getreg_b32 s2, hwreg(HW_REG_XCC_ID, 0, 4)
	s_addc_u32 s11, s13, 0
	s_and_b32 s33, s2, 15
	v_cmp_ne_u32_e64 s[6:7], 0, v210
	v_cmp_eq_u32_e64 s[8:9], 0, v210
	s_mov_b64 s[2:3], exec
	s_nop 0
	v_writelane_b32 v252, s8, 0
	s_nop 1
	v_writelane_b32 v252, s9, 1
	s_and_b64 s[8:9], s[2:3], s[8:9]
	s_mov_b64 exec, s[8:9]
	s_cbranch_execz .LBB0_5
	s_mov_b64 s[8:9], exec
	v_mbcnt_lo_u32_b32 v1, s8, 0
	v_mbcnt_hi_u32_b32 v1, s9, v1
	v_cmp_eq_u32_e32 vcc, 0, v1
	s_and_b64 s[14:15], exec, vcc
	s_mov_b64 exec, s[14:15]
	s_cbranch_execz .LBB0_5
	s_lshl_b32 s14, s33, 8
	s_bcnt1_i32_b64 s8, s[8:9]
	v_mov_b32_e32 v1, s14
	v_mov_b32_e32 v2, s8
	global_atomic_add v1, v2, s[10:11] offset:1024

	.amdhsa_kernel _Z14fwd_megakernel4Args
		.amdhsa_group_segment_fixed_size 0
		.amdhsa_private_segment_fixed_size 0
		.amdhsa_kernarg_size 408
		.amdhsa_user_sgpr_count 2
		.amdhsa_user_sgpr_dispatch_ptr 0
		.amdhsa_user_sgpr_queue_ptr 0
		.amdhsa_user_sgpr_kernarg_segment_ptr 1
		.amdhsa_user_sgpr_dispatch_id 0
		.amdhsa_user_sgpr_kernarg_preload_length 0
		.amdhsa_user_sgpr_kernarg_preload_offset 0
		.amdhsa_user_sgpr_private_segment_size 0
		.amdhsa_uses_dynamic_stack 0
		.amdhsa_enable_private_segment 0
		.amdhsa_system_sgpr_workgroup_id_x 1
		.amdhsa_system_sgpr_workgroup_id_y 0
		.amdhsa_system_sgpr_workgroup_id_z 0
		.amdhsa_system_sgpr_workgroup_info 0
		.amdhsa_system_vgpr_workitem_id 2
		.amdhsa_next_free_vgpr 253
		.amdhsa_next_free_sgpr 100
		.amdhsa_accum_offset 256
		.amdhsa_reserve_vcc 1
		.amdhsa_float_round_mode_32 0
		.amdhsa_float_round_mode_16_64 0
		.amdhsa_float_denorm_mode_32 3
		.amdhsa_float_denorm_mode_16_64 3
		.amdhsa_dx10_clamp 1
		.amdhsa_ieee_mode 1
		.amdhsa_fp16_overflow 0
		.amdhsa_tg_split 0
		.amdhsa_exception_fp_ieee_invalid_op 0
		.amdhsa_exception_fp_denorm_src 0
		.amdhsa_exception_fp_ieee_div_zero 0
		.amdhsa_exception_fp_ieee_overflow 0
		.amdhsa_exception_fp_ieee_underflow 0
		.amdhsa_exception_fp_ieee_inexact 0
		.amdhsa_exception_int_div_zero 0
	.end_amdhsa_kernel

amdhsa.kernels:
  - .agpr_count:     0
    .args:
      - .offset:         0
        .size:           152
        .value_kind:     by_value
      - .offset:         152
        .size:           4
        .value_kind:     hidden_block_count_x
      - .offset:         156
        .size:           4
        .value_kind:     hidden_block_count_y
      - .offset:         160
        .size:           4
        .value_kind:     hidden_block_count_z
      - .offset:         164
        .size:           2
        .value_kind:     hidden_group_size_x
      - .offset:         166
        .size:           2
        .value_kind:     hidden_group_size_y
      - .offset:         168
        .size:           2
        .value_kind:     hidden_group_size_z
      - .offset:         170
        .size:           2
        .value_kind:     hidden_remainder_x
      - .offset:         172
        .size:           2
        .value_kind:     hidden_remainder_y
      - .offset:         174
        .size:           2
        .value_kind:     hidden_remainder_z
      - .offset:         192
        .size:           8
        .value_kind:     hidden_global_offset_x
      - .offset:         200
        .size:           8
        .value_kind:     hidden_global_offset_y
      - .offset:         208
        .size:           8
        .value_kind:     hidden_global_offset_z
      - .offset:         216
        .size:           2
        .value_kind:     hidden_grid_dims
      - .offset:         240
        .size:           8
        .value_kind:     hidden_multigrid_sync_arg
      - .offset:         272
        .size:           4
        .value_kind:     hidden_dynamic_lds_size
    .group_segment_fixed_size: 0
    .kernarg_segment_align: 8
    .kernarg_segment_size: 408
    .language:       OpenCL C
    .language_version:
      - 2
      - 0
    .max_flat_workgroup_size: 512
    .name:           _Z14fwd_megakernel4Args
    .private_segment_fixed_size: 0
    .sgpr_count:     106
    .sgpr_spill_count: 136
    .symbol:         _Z14fwd_megakernel4Args.kd
    .uniform_work_group_size: 1
    .uses_dynamic_stack: false
    .vgpr_count:     253
    .vgpr_spill_count: 0
    .wavefront_size: 64
